# GEMM K-loop: A0 fragment LDS reads issued one load segment earlier (read counts per segment 12/4/8/0 -> 8/4/8/4), LDS-DMA completion wait moved with them as counted vmcnt(10)
# speedup vs baseline: 1.0131x; 1.0035x over previous
; #define PG8_STAGE(bufoff, gbase, voff) do { _Pragma("unroll") for (int _i = 0; _i < 2; ++_i) \
;         __builtin_amdgcn_global_load_lds((const unsigned*)((const char*)(gbase) + (voff)[_i]), (LAS unsigned*)(lds + (bufoff) + ldsw + _i * 8192), 16, 0, 0); } while (0)
; #define PG8_LDA(dst, b, h) do { _Pragma("unroll") for (int m = 0; m < 4; ++m) _Pragma("unroll") for (int k = 0; k < 2; ++k) dst[m][k] = *(const LAS f16x8*)(lds + PG8_SA(b, h) + aoff + m * 2048 + k * 1024); } while (0)
; #define PG8_LDB(dst, b, h) do { _Pragma("unroll") for (int n = 0; n < 2; ++n) _Pragma("unroll") for (int k = 0; k < 2; ++k) dst[n][k] = *(const LAS f16x8*)(lds + PG8_SB(b, h) + boff + n * 2048 + k * 1024); } while (0)
; #define PG8_WAIT_L(n) asm volatile("s_waitcnt lgkmcnt(" #n ")" ::: "memory")
; #define PG8_BAR __builtin_amdgcn_s_barrier()
; #define PG8_SCHED __builtin_amdgcn_sched_barrier(0)
; template <class Epi, class Sched>
; __device__ __forceinline__ void gemm_phase(LAS unsigned char* lds, const Gemm g, const Sched& S, const Epi& E) {
;     ...
;     for (;;) {
;         const bool has_next = S.next(ui + 1, nxt);
;         const char* nA = has_next ? (const char*)g.A + (size_t)nxt.pm * tstep + (size_t)(nxt.k0 < 0 ? -1 - nxt.k0 : nxt.k0) * kstep : cA; const char* nB = has_next ? (const char*)g.Bt + (size_t)nxt.pn * tstep + (size_t)(nxt.k0 < 0 ? -1 - nxt.k0 : nxt.k0) * kstep : cB;
;         const int nt = cur.nt;
;         for (int t = 0; t < nt; t += 2) {
;             const bool last = (t == nt - 2);
;             const char* a1 = cA + (size_t)(t + 1) * kstep;
;             const char* a2 = last ? nA : cA + (size_t)(t + 2) * kstep; const char* b2 = last ? nB : cB + (size_t)(t + 2) * kstep;
;             const char* a3 = a2 + kstep; const char* b3 = b2 + kstep;
;             if (last && has_next) S.a_ready(nxt);
;             PG8_LDB(B0, 0, 0); PG8_SCHED; PG8_LDA(At, 0, 0); PG8_STAGE(PG8_SA(1, 1), a1 + hstep, voffA);
;             PG8_WAIT_L(8); PG8_BAR; PG8_WAIT_L(0); PG8_MMA(0, 0, At, B0); PG8_BAR; PG8_SCHED;
;     ...
; #pragma unroll
;         for (int a = 0; a < 2; ++a)
; #pragma unroll
;             for (int b = 0; b < 2; ++b)
; #pragma unroll
;                 for (int m = 0; m < 4; ++m)
; #pragma unroll
;                     for (int n = 0; n < 2; ++n) acc[a][b][m][n] = (f32x4){0.f, 0.f, 0.f, 0.f};
.LBB0_828:
	s_xor_b64 s[4:5], s[4:5], -1
	s_add_i32 s40, s77, -2
	s_add_u32 s6, s6, 0x80
	s_addc_u32 s7, s7, 0
	s_add_u32 s41, s8, 0x100
	v_mov_b32_e32 v0, 0
	s_addc_u32 vcc_lo, s9, 0
	s_mov_b32 s8, 0
	v_mov_b32_e32 v1, v0
	v_mov_b32_e32 v2, v0
	v_mov_b32_e32 v3, v0
	v_mov_b32_e32 v4, v0
	v_mov_b32_e32 v5, v0
	v_mov_b32_e32 v6, v0
	v_mov_b32_e32 v7, v0
	v_mov_b32_e32 v18, v0
	v_mov_b32_e32 v19, v0
	v_mov_b32_e32 v20, v0
	v_mov_b32_e32 v21, v0
	v_mov_b32_e32 v22, v0
	v_mov_b32_e32 v23, v0
	v_mov_b32_e32 v24, v0
	v_mov_b32_e32 v25, v0
	v_mov_b32_e32 v34, v0
	v_mov_b32_e32 v35, v0
	v_mov_b32_e32 v36, v0
	v_mov_b32_e32 v37, v0
	v_mov_b32_e32 v38, v0
	v_mov_b32_e32 v39, v0
	v_mov_b32_e32 v40, v0
	v_mov_b32_e32 v41, v0
	v_mov_b32_e32 v50, v0
	v_mov_b32_e32 v51, v0
	v_mov_b32_e32 v52, v0
	v_mov_b32_e32 v53, v0
	v_mov_b32_e32 v54, v0
	v_mov_b32_e32 v55, v0
	v_mov_b32_e32 v56, v0
	v_mov_b32_e32 v57, v0
	v_mov_b32_e32 v8, v0
	v_mov_b32_e32 v9, v0
	v_mov_b32_e32 v10, v0
	v_mov_b32_e32 v11, v0
	v_mov_b32_e32 v12, v0
	v_mov_b32_e32 v13, v0
	v_mov_b32_e32 v14, v0
	v_mov_b32_e32 v15, v0
	v_mov_b32_e32 v26, v0
	v_mov_b32_e32 v27, v0
	v_mov_b32_e32 v28, v0
	v_mov_b32_e32 v29, v0
	v_mov_b32_e32 v30, v0
	v_mov_b32_e32 v31, v0
	v_mov_b32_e32 v32, v0
	v_mov_b32_e32 v33, v0
	v_mov_b32_e32 v42, v0
	v_mov_b32_e32 v43, v0
	v_mov_b32_e32 v44, v0
	v_mov_b32_e32 v45, v0
	v_mov_b32_e32 v46, v0
	v_mov_b32_e32 v47, v0
	v_mov_b32_e32 v48, v0
	v_mov_b32_e32 v49, v0
	v_mov_b32_e32 v58, v0
	v_mov_b32_e32 v59, v0
	v_mov_b32_e32 v60, v0
	v_mov_b32_e32 v61, v0
	v_mov_b32_e32 v62, v0
	v_mov_b32_e32 v63, v0
	v_mov_b32_e32 v64, v0
	v_mov_b32_e32 v65, v0
	v_mov_b32_e32 v66, v0
	v_mov_b32_e32 v67, v0
	v_mov_b32_e32 v68, v0
	v_mov_b32_e32 v69, v0
	v_mov_b32_e32 v70, v0
	v_mov_b32_e32 v71, v0
	v_mov_b32_e32 v72, v0
	v_mov_b32_e32 v73, v0
	v_mov_b32_e32 v82, v0
	v_mov_b32_e32 v83, v0
	v_mov_b32_e32 v84, v0
	v_mov_b32_e32 v85, v0
	v_mov_b32_e32 v86, v0
	v_mov_b32_e32 v87, v0
	v_mov_b32_e32 v88, v0
	v_mov_b32_e32 v89, v0
	v_mov_b32_e32 v98, v0
	v_mov_b32_e32 v99, v0
	v_mov_b32_e32 v100, v0
	v_mov_b32_e32 v101, v0
	v_mov_b32_e32 v102, v0
	v_mov_b32_e32 v103, v0
	v_mov_b32_e32 v104, v0
	v_mov_b32_e32 v105, v0
	v_mov_b32_e32 v114, v0
	v_mov_b32_e32 v115, v0
	v_mov_b32_e32 v116, v0
	v_mov_b32_e32 v117, v0
	v_mov_b32_e32 v118, v0
	v_mov_b32_e32 v119, v0
	v_mov_b32_e32 v120, v0
	v_mov_b32_e32 v121, v0
	v_mov_b32_e32 v74, v0
	v_mov_b32_e32 v75, v0
	v_mov_b32_e32 v76, v0
	v_mov_b32_e32 v77, v0
	v_mov_b32_e32 v78, v0
	v_mov_b32_e32 v79, v0
	v_mov_b32_e32 v80, v0
	v_mov_b32_e32 v81, v0
	v_mov_b32_e32 v90, v0
	v_mov_b32_e32 v91, v0
	v_mov_b32_e32 v92, v0
	v_mov_b32_e32 v93, v0
	v_mov_b32_e32 v94, v0
	v_mov_b32_e32 v95, v0
	v_mov_b32_e32 v96, v0
	v_mov_b32_e32 v97, v0
	v_mov_b32_e32 v106, v0
	v_mov_b32_e32 v107, v0
	v_mov_b32_e32 v108, v0
	v_mov_b32_e32 v109, v0
	v_mov_b32_e32 v110, v0
	v_mov_b32_e32 v111, v0
	v_mov_b32_e32 v112, v0
	v_mov_b32_e32 v113, v0
	v_mov_b32_e32 v122, v0
	v_mov_b32_e32 v123, v0
	v_mov_b32_e32 v124, v0
	v_mov_b32_e32 v125, v0
	v_mov_b32_e32 v126, v0
	v_mov_b32_e32 v127, v0
	v_mov_b32_e32 v128, v0
	v_mov_b32_e32 v129, v0
	v_add_u32_e32 v16, 0x10000, v159
	ds_read_b128 v[144:147], v16
	ds_read_b128 v[148:151], v16 offset:1024
	ds_read_b128 v[152:155], v16 offset:2048
	ds_read_b128 v[162:165], v16 offset:3072
.LBB0_829:
	s_add_i32 vcc_hi, s8, 2
	s_add_u32 s10, s6, 0x80
	s_addc_u32 s9, s7, 0
	s_add_i32 s17, 0, 0x10000
	s_cmp_eq_u32 s40, s8
	s_cselect_b32 s8, s66, s10
	s_cselect_b32 s9, s67, s9
	s_cselect_b32 s11, s69, vcc_lo
	s_cselect_b32 s10, s68, s41
	v_lshl_add_u64 v[156:157], s[6:7], 0, v[140:141]
	s_add_i32 m0, s82, 0xc000
	ds_read_b128 v[166:169], v161
	ds_read_b128 v[170:173], v161 offset:1024
	ds_read_b128 v[174:177], v161 offset:2048
	ds_read_b128 v[178:181], v161 offset:3072
	ds_read_b128 v[182:185], v161 offset:4096
	ds_read_b128 v[186:189], v161 offset:5120
	ds_read_b128 v[190:193], v161 offset:6144
	ds_read_b128 v[194:197], v161 offset:7168
	global_load_lds_dwordx4 v[156:157], off
	v_lshl_add_u64 v[156:157], s[6:7], 0, v[142:143]
	s_add_i32 m0, s82, 0xe000
	s_nop 0
	global_load_lds_dwordx4 v[156:157], off
	s_waitcnt lgkmcnt(8)
	s_barrier
	s_waitcnt lgkmcnt(0)
	s_setprio 1
	s_waitcnt lgkmcnt(0)
	v_mfma_f32_16x16x32_f16 v[126:129], v[144:147], v[166:169], v[126:129]
	v_mfma_f32_16x16x32_f16 v[122:125], v[152:155], v[166:169], v[122:125]
	v_mfma_f32_16x16x32_f16 v[110:113], v[144:147], v[174:177], v[110:113]
	v_mfma_f32_16x16x32_f16 v[106:109], v[152:155], v[174:177], v[106:109]
	v_mfma_f32_16x16x32_f16 v[94:97], v[144:147], v[182:185], v[94:97]
	v_mfma_f32_16x16x32_f16 v[90:93], v[152:155], v[182:185], v[90:93]
	v_mfma_f32_16x16x32_f16 v[78:81], v[144:147], v[190:193], v[78:81]
	v_mfma_f32_16x16x32_f16 v[74:77], v[152:155], v[190:193], v[74:77]
	v_mfma_f32_16x16x32_f16 v[126:129], v[148:151], v[170:173], v[126:129]
	v_mfma_f32_16x16x32_f16 v[122:125], v[162:165], v[170:173], v[122:125]
	v_mfma_f32_16x16x32_f16 v[110:113], v[148:151], v[178:181], v[110:113]
	v_mfma_f32_16x16x32_f16 v[106:109], v[162:165], v[178:181], v[106:109]
	v_mfma_f32_16x16x32_f16 v[94:97], v[148:151], v[186:189], v[94:97]
	v_mfma_f32_16x16x32_f16 v[90:93], v[162:165], v[186:189], v[90:93]
	v_mfma_f32_16x16x32_f16 v[78:81], v[148:151], v[194:197], v[78:81]
	v_mfma_f32_16x16x32_f16 v[74:77], v[162:165], v[194:197], v[74:77]
	s_setprio 0
	s_barrier
	s_add_i32 s86, 0, 0x14000
	s_add_i32 s17, s17, s71
	v_add_u32_e32 v16, s86, v159
	v_lshl_add_u64 v[156:157], s[10:11], 0, v[136:137]
	s_mov_b32 m0, s17
	ds_read_b128 v[198:201], v16
	ds_read_b128 v[230:233], v16 offset:1024
	ds_read_b128 v[234:237], v16 offset:2048
	ds_read_b128 v[238:241], v16 offset:3072
	global_load_lds_dwordx4 v[156:157], off
	v_lshl_add_u64 v[242:243], s[10:11], 0, v[132:133]
	s_add_i32 m0, s17, 0x2000
	s_nop 0
	global_load_lds_dwordx4 v[242:243], off
	s_barrier
; #define PG8_STAGE(bufoff, gbase, voff) do { _Pragma("unroll") for (int _i = 0; _i < 2; ++_i) \
;         __builtin_amdgcn_global_load_lds((const unsigned*)((const char*)(gbase) + (voff)[_i]), (LAS unsigned*)(lds + (bufoff) + ldsw + _i * 8192), 16, 0, 0); } while (0)
; #define PG8_LDA(dst, b, h) do { _Pragma("unroll") for (int m = 0; m < 4; ++m) _Pragma("unroll") for (int k = 0; k < 2; ++k) dst[m][k] = *(const LAS f16x8*)(lds + PG8_SA(b, h) + aoff + m * 2048 + k * 1024); } while (0)
; #define PG8_LDB(dst, b, h) do { _Pragma("unroll") for (int n = 0; n < 2; ++n) _Pragma("unroll") for (int k = 0; k < 2; ++k) dst[n][k] = *(const LAS f16x8*)(lds + PG8_SB(b, h) + boff + n * 2048 + k * 1024); } while (0)
; #define PG8_MMA(ai, bj, At, Bt) do { __builtin_amdgcn_s_setprio(1); _Pragma("unroll") for (int m = 0; m < 4; ++m) _Pragma("unroll") for (int n = 0; n < 2; ++n) _Pragma("unroll") for (int k = 0; k < 2; ++k) \
;         acc[ai][bj][m][n] = __builtin_amdgcn_mfma_f32_16x16x32_f16(Bt[n][k], At[m][k], acc[ai][bj][m][n], 0, 0, 0); __builtin_amdgcn_s_setprio(0); } while (0)
; #define PG8_WAIT_V(n) asm volatile("s_waitcnt vmcnt(" #n ")" ::: "memory")
; #define PG8_WAIT_L(n) asm volatile("s_waitcnt lgkmcnt(" #n ")" ::: "memory")
; #define PG8_BAR __builtin_amdgcn_s_barrier()
; #define PG8_SCHED __builtin_amdgcn_sched_barrier(0)
; template <class Epi, class Sched>
; __device__ __forceinline__ void gemm_phase(LAS unsigned char* lds, const Gemm g, const Sched& S, const Epi& E) {
;     ...
;             PG8_BAR; PG8_WAIT_L(0); PG8_MMA(0, 1, At, B1); PG8_BAR;
;             PG8_LDA(At, 0, 1); PG8_STAGE(PG8_SA(0, 0), a2, voffA);
;             PG8_BAR; PG8_WAIT_L(0); PG8_MMA(1, 0, At, B0); PG8_BAR; PG8_SCHED;
;             PG8_STAGE(PG8_SB(0, 1), b2 + hstep, voffB);
;             PG8_WAIT_V(6); PG8_BAR; PG8_MMA(1, 1, At, B1); PG8_BAR;
;             PG8_LDB(B0, 1, 0); PG8_SCHED; PG8_LDA(At, 1, 0); PG8_STAGE(PG8_SA(0, 1), a2 + hstep, voffA);
;             PG8_WAIT_L(8); PG8_BAR; PG8_WAIT_L(0); PG8_MMA(0, 0, At, B0); PG8_BAR; PG8_SCHED;
	s_waitcnt lgkmcnt(0)
	s_setprio 1
	s_waitcnt lgkmcnt(0)
	v_mfma_f32_16x16x32_f16 v[118:121], v[198:201], v[166:169], v[118:121]
	v_mfma_f32_16x16x32_f16 v[114:117], v[234:237], v[166:169], v[114:117]
	v_mfma_f32_16x16x32_f16 v[102:105], v[198:201], v[174:177], v[102:105]
	v_mfma_f32_16x16x32_f16 v[98:101], v[234:237], v[174:177], v[98:101]
	v_mfma_f32_16x16x32_f16 v[86:89], v[198:201], v[182:185], v[86:89]
	v_mfma_f32_16x16x32_f16 v[82:85], v[234:237], v[182:185], v[82:85]
	v_mfma_f32_16x16x32_f16 v[70:73], v[198:201], v[190:193], v[70:73]
	v_mfma_f32_16x16x32_f16 v[66:69], v[234:237], v[190:193], v[66:69]
	v_mfma_f32_16x16x32_f16 v[118:121], v[230:233], v[170:173], v[118:121]
	v_mfma_f32_16x16x32_f16 v[114:117], v[238:241], v[170:173], v[114:117]
	v_mfma_f32_16x16x32_f16 v[102:105], v[230:233], v[178:181], v[102:105]
	v_mfma_f32_16x16x32_f16 v[98:101], v[238:241], v[178:181], v[98:101]
	v_mfma_f32_16x16x32_f16 v[86:89], v[230:233], v[186:189], v[86:89]
	v_mfma_f32_16x16x32_f16 v[82:85], v[238:241], v[186:189], v[82:85]
	v_mfma_f32_16x16x32_f16 v[70:73], v[230:233], v[194:197], v[70:73]
	v_mfma_f32_16x16x32_f16 v[66:69], v[238:241], v[194:197], v[66:69]
	s_setprio 0
	s_mov_b32 m0, s82
	v_lshl_add_u64 v[244:245], s[8:9], 0, v[134:135]
	s_barrier
	ds_read_b128 v[166:169], v161 offset:16384
	ds_read_b128 v[170:173], v161 offset:17408
	ds_read_b128 v[174:177], v161 offset:18432
	ds_read_b128 v[178:181], v161 offset:19456
	ds_read_b128 v[182:185], v161 offset:20480
	ds_read_b128 v[186:189], v161 offset:21504
	ds_read_b128 v[190:193], v161 offset:22528
	ds_read_b128 v[194:197], v161 offset:23552
	global_load_lds_dwordx4 v[244:245], off
	v_lshl_add_u64 v[246:247], s[8:9], 0, v[130:131]
	s_mov_b32 m0, s83
	s_nop 0
	global_load_lds_dwordx4 v[246:247], off
	s_waitcnt vmcnt(10)
	s_barrier
	s_waitcnt lgkmcnt(0)
	s_setprio 1
	s_waitcnt lgkmcnt(0)
	v_mfma_f32_16x16x32_f16 v[62:65], v[144:147], v[166:169], v[62:65]
	v_mfma_f32_16x16x32_f16 v[58:61], v[152:155], v[166:169], v[58:61]
	v_mfma_f32_16x16x32_f16 v[46:49], v[144:147], v[174:177], v[46:49]
	v_mfma_f32_16x16x32_f16 v[42:45], v[152:155], v[174:177], v[42:45]
	v_mfma_f32_16x16x32_f16 v[30:33], v[144:147], v[182:185], v[30:33]
	v_mfma_f32_16x16x32_f16 v[26:29], v[152:155], v[182:185], v[26:29]
	v_mfma_f32_16x16x32_f16 v[12:15], v[144:147], v[190:193], v[12:15]
	v_mfma_f32_16x16x32_f16 v[8:11], v[152:155], v[190:193], v[8:11]
	v_mfma_f32_16x16x32_f16 v[62:65], v[148:151], v[170:173], v[62:65]
	v_mfma_f32_16x16x32_f16 v[58:61], v[162:165], v[170:173], v[58:61]
	v_mfma_f32_16x16x32_f16 v[46:49], v[148:151], v[178:181], v[46:49]
	v_mfma_f32_16x16x32_f16 v[42:45], v[162:165], v[178:181], v[42:45]
	v_mfma_f32_16x16x32_f16 v[30:33], v[148:151], v[186:189], v[30:33]
	v_mfma_f32_16x16x32_f16 v[26:29], v[162:165], v[186:189], v[26:29]
	v_mfma_f32_16x16x32_f16 v[12:15], v[148:151], v[194:197], v[12:15]
	v_mfma_f32_16x16x32_f16 v[8:11], v[162:165], v[194:197], v[8:11]
	s_setprio 0
	s_barrier
	v_add_u32_e32 v16, 0x18000, v159
	ds_read_b128 v[144:147], v16
	ds_read_b128 v[148:151], v16 offset:1024
	ds_read_b128 v[152:155], v16 offset:2048
	ds_read_b128 v[162:165], v16 offset:3072
	s_add_u32 s10, s10, s44
	s_addc_u32 s11, s11, 0
	s_add_i32 s17, s86, s71
	v_lshl_add_u64 v[248:249], s[10:11], 0, v[136:137]
	s_mov_b32 m0, s17
	v_lshl_add_u64 v[250:251], s[10:11], 0, v[132:133]
	global_load_lds_dwordx4 v[248:249], off
	s_add_i32 m0, s17, 0x2000
	s_nop 0
	global_load_lds_dwordx4 v[250:251], off
	s_waitcnt vmcnt(6)
	s_barrier
	s_setprio 1
	v_mfma_f32_16x16x32_f16 v[54:57], v[198:201], v[166:169], v[54:57]
	v_mfma_f32_16x16x32_f16 v[50:53], v[234:237], v[166:169], v[50:53]
	v_mfma_f32_16x16x32_f16 v[38:41], v[198:201], v[174:177], v[38:41]
	v_mfma_f32_16x16x32_f16 v[34:37], v[234:237], v[174:177], v[34:37]
	v_mfma_f32_16x16x32_f16 v[22:25], v[198:201], v[182:185], v[22:25]
	v_mfma_f32_16x16x32_f16 v[18:21], v[234:237], v[182:185], v[18:21]
	v_mfma_f32_16x16x32_f16 v[4:7], v[198:201], v[190:193], v[4:7]
	v_mfma_f32_16x16x32_f16 v[0:3], v[234:237], v[190:193], v[0:3]
	v_mfma_f32_16x16x32_f16 v[54:57], v[230:233], v[170:173], v[54:57]
	v_mfma_f32_16x16x32_f16 v[50:53], v[238:241], v[170:173], v[50:53]
	v_mfma_f32_16x16x32_f16 v[38:41], v[230:233], v[178:181], v[38:41]
	v_mfma_f32_16x16x32_f16 v[34:37], v[238:241], v[178:181], v[34:37]
	v_mfma_f32_16x16x32_f16 v[22:25], v[230:233], v[186:189], v[22:25]
	v_mfma_f32_16x16x32_f16 v[18:21], v[238:241], v[186:189], v[18:21]
	v_mfma_f32_16x16x32_f16 v[4:7], v[230:233], v[194:197], v[4:7]
	v_mfma_f32_16x16x32_f16 v[0:3], v[238:241], v[194:197], v[0:3]
	s_setprio 0
	s_add_i32 s10, 0, 0x18000
	s_barrier
	s_add_u32 s8, s8, s44
	s_addc_u32 s9, s9, 0
	s_mov_b32 m0, s84
	v_lshl_add_u64 v[198:199], s[8:9], 0, v[134:135]
	ds_read_b128 v[166:169], v161 offset:32768
	ds_read_b128 v[170:173], v161 offset:33792
	ds_read_b128 v[174:177], v161 offset:34816
	ds_read_b128 v[178:181], v161 offset:35840
	ds_read_b128 v[182:185], v161 offset:36864
	ds_read_b128 v[186:189], v161 offset:37888
	ds_read_b128 v[190:193], v161 offset:38912
	ds_read_b128 v[194:197], v161 offset:39936
	global_load_lds_dwordx4 v[198:199], off
	v_lshl_add_u64 v[198:199], s[8:9], 0, v[130:131]
	s_mov_b32 m0, s85
	s_nop 0
	global_load_lds_dwordx4 v[198:199], off
	s_waitcnt lgkmcnt(8)
	s_barrier
; #define PG8_STAGE(bufoff, gbase, voff) do { _Pragma("unroll") for (int _i = 0; _i < 2; ++_i) \
;         __builtin_amdgcn_global_load_lds((const unsigned*)((const char*)(gbase) + (voff)[_i]), (LAS unsigned*)(lds + (bufoff) + ldsw + _i * 8192), 16, 0, 0); } while (0)
; #define PG8_LDA(dst, b, h) do { _Pragma("unroll") for (int m = 0; m < 4; ++m) _Pragma("unroll") for (int k = 0; k < 2; ++k) dst[m][k] = *(const LAS f16x8*)(lds + PG8_SA(b, h) + aoff + m * 2048 + k * 1024); } while (0)
; #define PG8_LDB(dst, b, h) do { _Pragma("unroll") for (int n = 0; n < 2; ++n) _Pragma("unroll") for (int k = 0; k < 2; ++k) dst[n][k] = *(const LAS f16x8*)(lds + PG8_SB(b, h) + boff + n * 2048 + k * 1024); } while (0)
; #define PG8_MMA(ai, bj, At, Bt) do { __builtin_amdgcn_s_setprio(1); _Pragma("unroll") for (int m = 0; m < 4; ++m) _Pragma("unroll") for (int n = 0; n < 2; ++n) _Pragma("unroll") for (int k = 0; k < 2; ++k) \
;         acc[ai][bj][m][n] = __builtin_amdgcn_mfma_f32_16x16x32_f16(Bt[n][k], At[m][k], acc[ai][bj][m][n], 0, 0, 0); __builtin_amdgcn_s_setprio(0); } while (0)
; #define PG8_WAIT_L(n) asm volatile("s_waitcnt lgkmcnt(" #n ")" ::: "memory")
; #define PG8_BAR __builtin_amdgcn_s_barrier()
; #define PG8_SCHED __builtin_amdgcn_sched_barrier(0)
; template <class Epi, class Sched>
; __device__ __forceinline__ void gemm_phase(LAS unsigned char* lds, const Gemm g, const Sched& S, const Epi& E) {
;     ...
;             PG8_WAIT_L(8); PG8_BAR; PG8_WAIT_L(0); PG8_MMA(0, 0, At, B0); PG8_BAR; PG8_SCHED;
;             PG8_LDB(B1, 1, 1); PG8_STAGE(PG8_SB(1, 0), b3, voffB);
;             PG8_BAR; PG8_WAIT_L(0); PG8_MMA(0, 1, At, B1); PG8_BAR;
;             PG8_LDA(At, 1, 1); PG8_STAGE(PG8_SA(1, 0), a3, voffA);
;             PG8_BAR; PG8_WAIT_L(0); PG8_MMA(1, 0, At, B0); PG8_BAR; PG8_SCHED;
	s_waitcnt lgkmcnt(0)
	s_setprio 1
	s_waitcnt lgkmcnt(0)
	v_mfma_f32_16x16x32_f16 v[126:129], v[144:147], v[166:169], v[126:129]
	v_mfma_f32_16x16x32_f16 v[122:125], v[152:155], v[166:169], v[122:125]
	v_mfma_f32_16x16x32_f16 v[110:113], v[144:147], v[174:177], v[110:113]
	v_mfma_f32_16x16x32_f16 v[106:109], v[152:155], v[174:177], v[106:109]
	v_mfma_f32_16x16x32_f16 v[94:97], v[144:147], v[182:185], v[94:97]
	v_mfma_f32_16x16x32_f16 v[90:93], v[152:155], v[182:185], v[90:93]
	v_mfma_f32_16x16x32_f16 v[78:81], v[144:147], v[190:193], v[78:81]
	v_mfma_f32_16x16x32_f16 v[74:77], v[152:155], v[190:193], v[74:77]
	v_mfma_f32_16x16x32_f16 v[126:129], v[148:151], v[170:173], v[126:129]
	v_mfma_f32_16x16x32_f16 v[122:125], v[162:165], v[170:173], v[122:125]
	v_mfma_f32_16x16x32_f16 v[110:113], v[148:151], v[178:181], v[110:113]
	v_mfma_f32_16x16x32_f16 v[106:109], v[162:165], v[178:181], v[106:109]
	v_mfma_f32_16x16x32_f16 v[94:97], v[148:151], v[186:189], v[94:97]
	v_mfma_f32_16x16x32_f16 v[90:93], v[162:165], v[186:189], v[90:93]
	v_mfma_f32_16x16x32_f16 v[78:81], v[148:151], v[194:197], v[78:81]
	v_mfma_f32_16x16x32_f16 v[74:77], v[162:165], v[194:197], v[74:77]
	s_setprio 0
	s_barrier
	s_add_i32 s8, 0, 0x1c000
	s_add_i32 s9, s10, s71
	v_add_u32_e32 v16, s8, v159
	v_lshl_add_u64 v[156:157], v[156:157], 0, s[90:91]
	s_mov_b32 m0, s9
	ds_read_b128 v[198:201], v16
	ds_read_b128 v[230:233], v16 offset:1024
	ds_read_b128 v[234:237], v16 offset:2048
	ds_read_b128 v[238:241], v16 offset:3072
	global_load_lds_dwordx4 v[156:157], off
	v_lshl_add_u64 v[156:157], v[242:243], 0, s[90:91]
	s_add_i32 m0, s9, 0x2000
	s_nop 0
	global_load_lds_dwordx4 v[156:157], off
	s_barrier
	s_waitcnt lgkmcnt(0)
	s_setprio 1
	s_waitcnt lgkmcnt(0)
	v_mfma_f32_16x16x32_f16 v[118:121], v[198:201], v[166:169], v[118:121]
	v_mfma_f32_16x16x32_f16 v[114:117], v[234:237], v[166:169], v[114:117]
	v_mfma_f32_16x16x32_f16 v[102:105], v[198:201], v[174:177], v[102:105]
	v_mfma_f32_16x16x32_f16 v[98:101], v[234:237], v[174:177], v[98:101]
	v_mfma_f32_16x16x32_f16 v[86:89], v[198:201], v[182:185], v[86:89]
	v_mfma_f32_16x16x32_f16 v[82:85], v[234:237], v[182:185], v[82:85]
	v_mfma_f32_16x16x32_f16 v[70:73], v[198:201], v[190:193], v[70:73]
	v_mfma_f32_16x16x32_f16 v[66:69], v[234:237], v[190:193], v[66:69]
	v_mfma_f32_16x16x32_f16 v[118:121], v[230:233], v[170:173], v[118:121]
	v_mfma_f32_16x16x32_f16 v[114:117], v[238:241], v[170:173], v[114:117]
	v_mfma_f32_16x16x32_f16 v[102:105], v[230:233], v[178:181], v[102:105]
	v_mfma_f32_16x16x32_f16 v[98:101], v[238:241], v[178:181], v[98:101]
	v_mfma_f32_16x16x32_f16 v[86:89], v[230:233], v[186:189], v[86:89]
	v_mfma_f32_16x16x32_f16 v[82:85], v[238:241], v[186:189], v[82:85]
	v_mfma_f32_16x16x32_f16 v[70:73], v[230:233], v[194:197], v[70:73]
	v_mfma_f32_16x16x32_f16 v[66:69], v[238:241], v[194:197], v[66:69]
	s_setprio 0
	s_mov_b32 m0, s94
	v_lshl_add_u64 v[156:157], v[244:245], 0, s[90:91]
	s_barrier
	ds_read_b128 v[166:169], v161 offset:49152
	ds_read_b128 v[170:173], v161 offset:50176
	ds_read_b128 v[174:177], v161 offset:51200
	ds_read_b128 v[178:181], v161 offset:52224
	ds_read_b128 v[182:185], v161 offset:53248
	ds_read_b128 v[186:189], v161 offset:54272
	ds_read_b128 v[190:193], v161 offset:55296
	ds_read_b128 v[194:197], v161 offset:56320
	global_load_lds_dwordx4 v[156:157], off
	v_lshl_add_u64 v[156:157], v[246:247], 0, s[90:91]
	s_mov_b32 m0, s95
	s_nop 0
	global_load_lds_dwordx4 v[156:157], off
	s_waitcnt vmcnt(10)
	s_barrier
; #define PG8_STAGE(bufoff, gbase, voff) do { _Pragma("unroll") for (int _i = 0; _i < 2; ++_i) \
;         __builtin_amdgcn_global_load_lds((const unsigned*)((const char*)(gbase) + (voff)[_i]), (LAS unsigned*)(lds + (bufoff) + ldsw + _i * 8192), 16, 0, 0); } while (0)
; #define PG8_LDA(dst, b, h) do { _Pragma("unroll") for (int m = 0; m < 4; ++m) _Pragma("unroll") for (int k = 0; k < 2; ++k) dst[m][k] = *(const LAS f16x8*)(lds + PG8_SA(b, h) + aoff + m * 2048 + k * 1024); } while (0)
; #define PG8_WAIT_V(n) asm volatile("s_waitcnt vmcnt(" #n ")" ::: "memory")
; #define PG8_WAIT_L(n) asm volatile("s_waitcnt lgkmcnt(" #n ")" ::: "memory")
; #define PG8_BAR __builtin_amdgcn_s_barrier()
; #define PG8_SCHED __builtin_amdgcn_sched_barrier(0)
;     __device__ __forceinline__ void operator()(const f32x4 (&acc)[2][2][4][2], const Unit& u, int wr, int wc, int fr, int fq) const {
;     ...
;             const int row0 = u.pm * BM + wr * 64 + fr; const int col0 = u.pn * BM + wc * 32 + 8 * fq;
;             const float lo = mode == 1 ? 0.f : -3.0e38f;
; #pragma unroll
;             for (int ai = 0; ai < 2; ++ai)
; #pragma unroll
;                 for (int m = 0; m < 4; ++m) { f16_t* rowp = O + (size_t)(row0 + ai * HALF + m * 16) * ldc + col0;
; #pragma unroll
;                     for (int bj = 0; bj < 2; ++bj) { f32x4 v0 = acc[ai][bj][m][0], v1 = acc[ai][bj][m][1];
;                         if (mode == 1) {
; #pragma unroll
;                             for (int j = 0; j < 4; ++j) { float a = fmaxf(v0[j], lo), b = fmaxf(v1[j], lo); v0[j] = a * a; v1[j] = b * b; } }
;                         u32x4 w; w.x = pkh(v0[0], v0[1]); w.y = pkh(v0[2], v0[3]); w.z = pkh(v1[0], v1[1]); w.w = pkh(v1[2], v1[3]);
;                         *(u32x4*)(rowp + bj * HALF) = w; } }
; template <class Epi, class Sched>
; __device__ __forceinline__ void gemm_phase(LAS unsigned char* lds, const Gemm g, const Sched& S, const Epi& E) {
;     ...
;             PG8_BAR; PG8_WAIT_L(0); PG8_MMA(0, 1, At, B1); PG8_BAR;
;             PG8_LDA(At, 1, 1); PG8_STAGE(PG8_SA(1, 0), a3, voffA);
;             PG8_BAR; PG8_WAIT_L(0); PG8_MMA(1, 0, At, B0); PG8_BAR; PG8_SCHED;
;             PG8_STAGE(PG8_SB(1, 1), b3 + hstep, voffB);
;             PG8_WAIT_V(6); PG8_BAR; PG8_MMA(1, 1, At, B1); PG8_BAR;
;         }
;         E(acc, cur, wr, wc, fr, fq); S.done(cur);
;         if (!has_next) break;
	s_waitcnt lgkmcnt(0)
	s_setprio 1
	s_waitcnt lgkmcnt(0)
	v_mfma_f32_16x16x32_f16 v[62:65], v[144:147], v[166:169], v[62:65]
	v_mfma_f32_16x16x32_f16 v[58:61], v[152:155], v[166:169], v[58:61]
	v_mfma_f32_16x16x32_f16 v[46:49], v[144:147], v[174:177], v[46:49]
	v_mfma_f32_16x16x32_f16 v[42:45], v[152:155], v[174:177], v[42:45]
	v_mfma_f32_16x16x32_f16 v[30:33], v[144:147], v[182:185], v[30:33]
	v_mfma_f32_16x16x32_f16 v[26:29], v[152:155], v[182:185], v[26:29]
	v_mfma_f32_16x16x32_f16 v[12:15], v[144:147], v[190:193], v[12:15]
	v_mfma_f32_16x16x32_f16 v[8:11], v[152:155], v[190:193], v[8:11]
	v_mfma_f32_16x16x32_f16 v[62:65], v[148:151], v[170:173], v[62:65]
	v_mfma_f32_16x16x32_f16 v[58:61], v[162:165], v[170:173], v[58:61]
	v_mfma_f32_16x16x32_f16 v[46:49], v[148:151], v[178:181], v[46:49]
	v_mfma_f32_16x16x32_f16 v[42:45], v[162:165], v[178:181], v[42:45]
	v_mfma_f32_16x16x32_f16 v[30:33], v[148:151], v[186:189], v[30:33]
	v_mfma_f32_16x16x32_f16 v[26:29], v[162:165], v[186:189], v[26:29]
	v_mfma_f32_16x16x32_f16 v[12:15], v[148:151], v[194:197], v[12:15]
	v_mfma_f32_16x16x32_f16 v[8:11], v[162:165], v[194:197], v[8:11]
	s_setprio 0
	s_barrier
	v_add_u32_e32 v16, 0x10000, v159
	ds_read_b128 v[144:147], v16
	ds_read_b128 v[148:151], v16 offset:1024
	ds_read_b128 v[152:155], v16 offset:2048
	ds_read_b128 v[162:165], v16 offset:3072
	s_add_i32 s8, s8, s71
	v_lshl_add_u64 v[156:157], v[248:249], 0, s[90:91]
	s_mov_b32 m0, s8
	s_nop 0
	global_load_lds_dwordx4 v[156:157], off
	v_lshl_add_u64 v[156:157], v[250:251], 0, s[90:91]
	s_add_i32 m0, s8, 0x2000
	s_nop 0
	global_load_lds_dwordx4 v[156:157], off
	s_waitcnt vmcnt(6)
	s_barrier
	s_setprio 1
	v_mfma_f32_16x16x32_f16 v[54:57], v[198:201], v[166:169], v[54:57]
	v_mfma_f32_16x16x32_f16 v[50:53], v[234:237], v[166:169], v[50:53]
	v_mfma_f32_16x16x32_f16 v[38:41], v[198:201], v[174:177], v[38:41]
	v_mfma_f32_16x16x32_f16 v[34:37], v[234:237], v[174:177], v[34:37]
	v_mfma_f32_16x16x32_f16 v[22:25], v[198:201], v[182:185], v[22:25]
	v_mfma_f32_16x16x32_f16 v[18:21], v[234:237], v[182:185], v[18:21]
	v_mfma_f32_16x16x32_f16 v[4:7], v[198:201], v[190:193], v[4:7]
	v_mfma_f32_16x16x32_f16 v[0:3], v[234:237], v[190:193], v[0:3]
	v_mfma_f32_16x16x32_f16 v[54:57], v[230:233], v[170:173], v[54:57]
	v_mfma_f32_16x16x32_f16 v[50:53], v[238:241], v[170:173], v[50:53]
	v_mfma_f32_16x16x32_f16 v[38:41], v[230:233], v[178:181], v[38:41]
	v_mfma_f32_16x16x32_f16 v[34:37], v[238:241], v[178:181], v[34:37]
	v_mfma_f32_16x16x32_f16 v[22:25], v[230:233], v[186:189], v[22:25]
	v_mfma_f32_16x16x32_f16 v[18:21], v[238:241], v[186:189], v[18:21]
	v_mfma_f32_16x16x32_f16 v[4:7], v[230:233], v[194:197], v[4:7]
	v_mfma_f32_16x16x32_f16 v[0:3], v[238:241], v[194:197], v[0:3]
	s_setprio 0
	s_add_u32 s6, s6, 0x100
	s_addc_u32 s7, s7, 0
	s_add_u32 s41, s41, 0x100
	s_addc_u32 vcc_lo, vcc_lo, 0
	s_cmp_ge_u32 vcc_hi, s77
	s_mov_b32 s8, vcc_hi
	s_barrier
	s_cbranch_scc0 .LBB0_829
	s_waitcnt lgkmcnt(0)
	v_lshl_add_u32 v162, s36, 8, v139
	v_ashrrev_i32_e32 v16, 31, v162
	s_lshl_b32 s3, s3, 8
	v_mul_lo_u32 v163, s54, v16
	v_mul_lo_u32 v16, s55, v162
	v_mad_u64_u32 v[144:145], s[6:7], s54, v162, 0
	s_or_b32 s3, s3, s89
	v_add3_u32 v145, v145, v163, v16
	s_mov_b64 s[6:7], -1
	s_and_b64 vcc, exec, s[42:43]
	s_movk_i32 s86, 0x41ff
	s_cbranch_vccz .LBB0_864
	v_cndmask_b32_e64 v16, 0, 1, s[48:49]
	v_cmp_ne_u32_e64 s[40:41], 1, v16
	s_andn2_b64 vcc, exec, s[48:49]
	v_or_b32_e32 v16, s3, v158
	v_lshlrev_b32_e32 v16, 1, v16
	v_lshl_add_u64 v[146:147], s[52:53], 0, v[16:17]
	v_lshl_add_u64 v[148:149], v[144:145], 1, v[146:147]
	s_cbranch_vccnz .Lep0_0
	v_max_f32_e32 v150, 0, v126
	v_max_f32_e32 v151, 0, v127
	v_max_f32_e32 v152, 0, v128
	v_max_f32_e32 v153, 0, v129
	v_max_f32_e32 v154, 0, v122
	v_max_f32_e32 v155, 0, v123
	v_max_f32_e32 v156, 0, v124
	v_max_f32_e32 v157, 0, v125
	v_pk_mul_f32 v[150:151], v[150:151], v[150:151]
	v_pk_mul_f32 v[152:153], v[152:153], v[152:153]
	v_pk_mul_f32 v[154:155], v[154:155], v[154:155]
	v_pk_mul_f32 v[156:157], v[156:157], v[156:157]
	v_cvt_pk_f16_f32 v150, v150, v151
	v_cvt_pk_f16_f32 v151, v152, v153
	v_cvt_pk_f16_f32 v152, v154, v155
	v_cvt_pk_f16_f32 v153, v156, v157
	s_branch .Lep1_0
